# in-proj k/v f32 cache stores transposed through LDS: 16 consecutive lanes write 256 contiguous bytes of a row (was 16 B pieces of 16 rows)
# speedup vs baseline: 1.0270x; 1.0103x over previous
.LBB0_607:
	s_add_u32 s42, s94, s42
	s_addc_u32 s43, s95, s43
	s_ashr_i32 s4, s4, 6
	s_and_b32 s4, s4, -4
	s_add_i32 s4, s4, s18
	v_lshlrev_b64 v[130:131], 8, v[130:131]
	s_ashr_i32 s5, s4, 31
	v_lshl_add_u64 v[130:131], s[42:43], 0, v[130:131]
	v_lshlrev_b32_e32 v132, 1, v217
	v_mov_b32_e32 v133, v1
	s_lshl_b64 s[4:5], s[4:5], 17
	v_lshl_add_u64 v[192:193], v[130:131], 0, v[132:133]
	s_add_u32 s4, s88, s4
	v_lshlrev_b32_e32 v130, 9, v190
	s_addc_u32 s5, s89, s5
	v_and_b32_e32 v130, 0x19e00, v130
	v_mov_b32_e32 v131, v1
	v_lshl_add_u64 v[130:131], s[4:5], 0, v[130:131]
	v_lshl_add_u64 v[130:131], v[130:131], 0, s[54:55]
	v_lshl_add_u64 v[194:195], v[130:131], 0, v[0:1]
	v_cndmask_b32_e64 v130, 0, 1, s[60:61]
	s_waitcnt vmcnt(0)
	s_barrier
	v_readfirstlane_b32 vcc_lo, v225
	s_lshr_b32 vcc_lo, vcc_lo, 6
	s_mulk_i32 vcc_lo, 0x1100
	s_mov_b32 m0, vcc_lo
	s_mov_b64 s[56:57], -1
	s_and_b64 vcc, exec, s[48:49]
	v_cmp_ne_u32_e64 s[42:43], 1, v130
	s_cbranch_vccz .LBB0_625
	global_load_dwordx4 v[130:133], v[188:189], off
	global_load_dwordx4 v[134:137], v[188:189], off offset:256
	global_load_dwordx4 v[138:141], v[188:189], off offset:512
	global_load_dwordx4 v[142:145], v[188:189], off offset:768
	global_load_dwordx4 v[228:231], v[188:189], off offset:2048
	global_load_dwordx4 v[232:235], v[188:189], off offset:2304
	global_load_dwordx4 v[240:243], v[188:189], off offset:2560
	global_load_dwordx4 v[158:161], v[188:189], off offset:2816
	global_load_dwordx4 v[244:247], v[186:187], off
	global_load_dwordx4 v[248:251], v[186:187], off offset:64
	global_load_dwordx4 v[150:153], v[186:187], off offset:512
	global_load_dwordx4 v[218:221], v[186:187], off offset:576
	v_mov_b64_e32 v[196:197], v[194:195]
	v_mov_b64_e32 v[176:177], v[192:193]
	s_and_b64 vcc, exec, s[42:43]
	s_waitcnt vmcnt(8)
	v_mov_b32_e32 v146, v131
	v_mov_b32_e32 v147, v132
	v_mov_b32_e32 v131, v133
	v_mov_b32_e32 v132, v135
	v_mov_b32_e32 v133, v136
	v_mov_b32_e32 v135, v137
	v_mov_b32_e32 v136, v139
	v_mov_b32_e32 v137, v140
	v_mov_b32_e32 v139, v141
	v_mov_b32_e32 v140, v143
	v_mov_b32_e32 v141, v144
	v_mov_b32_e32 v143, v145
	v_pk_add_f32 v[130:131], v[146:147], v[130:131]
	v_pk_add_f32 v[132:133], v[132:133], v[134:135]
	v_pk_add_f32 v[134:135], v[136:137], v[138:139]
	v_pk_add_f32 v[136:137], v[140:141], v[142:143]
	v_add_f32_e32 v130, v130, v131
	v_add_f32_e32 v131, v132, v133
	v_add_f32_e32 v132, v134, v135
	v_add_f32_e32 v133, v136, v137
	v_fmamk_f32 v130, v130, 0x3a800000, v223
	v_fmamk_f32 v131, v131, 0x3a800000, v223
	v_fmamk_f32 v132, v132, 0x3a800000, v223
	v_fmamk_f32 v133, v133, 0x3a800000, v223
	v_rsq_f32_e32 v148, v130
	v_rsq_f32_e32 v174, v131
	v_rsq_f32_e32 v172, v132
	v_rsq_f32_e32 v170, v133
	s_waitcnt vmcnt(7)
	v_add_f32_e32 v228, v228, v229
	v_add_f32_e32 v229, v230, v231
	s_waitcnt vmcnt(6)
	v_add_f32_e32 v230, v232, v233
	v_add_f32_e32 v231, v234, v235
	s_waitcnt vmcnt(5)
	v_add_f32_e32 v232, v240, v241
	v_add_f32_e32 v233, v242, v243
	s_waitcnt vmcnt(4)
	v_add_f32_e32 v234, v158, v159
	v_add_f32_e32 v235, v160, v161
	v_add_f32_e32 v228, v228, v229
	v_add_f32_e32 v229, v230, v231
	v_add_f32_e32 v230, v232, v233
	v_add_f32_e32 v231, v234, v235
	v_fmamk_f32 v228, v228, 0x3a800000, v223
	v_fmamk_f32 v229, v229, 0x3a800000, v223
	v_fmamk_f32 v230, v230, 0x3a800000, v223
	v_fmamk_f32 v231, v231, 0x3a800000, v223
	v_rsq_f32_e32 v168, v228
	v_rsq_f32_e32 v166, v229
	v_rsq_f32_e32 v164, v230
	v_rsq_f32_e32 v162, v231
	s_waitcnt vmcnt(3)
	v_mov_b64_e32 v[142:143], v[244:245]
	v_mov_b64_e32 v[144:145], v[246:247]
	v_pk_fma_f32 v[158:159], v[126:127], v[148:149], v[142:143] op_sel_hi:[1,0,1]
	v_pk_fma_f32 v[160:161], v[128:129], v[148:149], v[144:145] op_sel_hi:[1,0,1]
	s_waitcnt vmcnt(2)
	v_mov_b64_e32 v[138:139], v[248:249]
	v_mov_b64_e32 v[140:141], v[250:251]
	v_pk_fma_f32 v[154:155], v[122:123], v[148:149], v[138:139] op_sel_hi:[1,0,1]
	v_pk_fma_f32 v[156:157], v[124:125], v[148:149], v[140:141] op_sel_hi:[1,0,1]
	s_waitcnt vmcnt(1)
	v_mov_b64_e32 v[134:135], v[150:151]
	v_mov_b64_e32 v[136:137], v[152:153]
	v_pk_fma_f32 v[150:151], v[118:119], v[148:149], v[134:135] op_sel_hi:[1,0,1]
	v_pk_fma_f32 v[152:153], v[120:121], v[148:149], v[136:137] op_sel_hi:[1,0,1]
	s_waitcnt vmcnt(0)
	v_mov_b64_e32 v[130:131], v[218:219]
	v_mov_b64_e32 v[132:133], v[220:221]
	v_pk_fma_f32 v[146:147], v[114:115], v[148:149], v[130:131] op_sel_hi:[1,0,1]
	v_pk_fma_f32 v[148:149], v[116:117], v[148:149], v[132:133] op_sel_hi:[1,0,1]
	s_cbranch_vccnz .LBB0_610
	v_mbcnt_lo_u32_b32 v228, -1, 0
	v_mbcnt_hi_u32_b32 v228, -1, v228
	v_and_b32_e32 v229, 15, v228
	v_lshrrev_b32_e32 v228, 4, v228
	v_mul_u32_u24_e32 v230, 0x110, v229
	v_lshl_add_u32 v222, v228, 4, v230
	v_add_u32_e32 v222, m0, v222
	v_mul_u32_u24_e32 v230, 0x110, v228
	v_lshl_add_u32 v224, v229, 4, v230
	v_add_u32_e32 v224, m0, v224
	v_sub_u32_e32 v236, v228, v229
	v_mul_i32_i24_e32 v236, 0x1f0, v236
	v_ashrrev_i32_e32 v237, 31, v236
	ds_write_b128 v222, v[158:161]
	ds_write_b128 v222, v[154:157] offset:64
	ds_write_b128 v222, v[150:153] offset:128
	ds_write_b128 v222, v[146:149] offset:192
	v_lshl_add_u64 v[236:237], v[196:197], 0, v[236:237]
	ds_read_b128 v[228:231], v224
	ds_read_b128 v[232:235], v224 offset:1088
	s_waitcnt lgkmcnt(1)
	global_store_dwordx4 v[236:237], v[228:231], off
	s_waitcnt lgkmcnt(0)
	global_store_dwordx4 v[236:237], v[232:235], off offset:2048
	v_add_co_u32_e32 v236, vcc, 0x1000, v236
	s_nop 1
	v_addc_co_u32_e32 v237, vcc, 0, v237, vcc
	ds_read_b128 v[228:231], v224 offset:2176
	ds_read_b128 v[232:235], v224 offset:3264
	s_waitcnt lgkmcnt(1)
	global_store_dwordx4 v[236:237], v[228:231], off
	s_waitcnt lgkmcnt(0)
	global_store_dwordx4 v[236:237], v[232:235], off offset:2048
.LBB0_610:
	v_cvt_pk_bf16_f32 v240, v158, v159
	v_cvt_pk_bf16_f32 v241, v160, v161
	v_mbcnt_lo_u32_b32 v0, -1, 0
	v_mbcnt_hi_u32_b32 v0, -1, v0
	v_bfe_u32 v0, v0, 4, 1
	v_mul_u32_u24_e32 v0, 24, v0
	v_lshl_add_u64 v[248:249], v[176:177], 0, v[0:1]
	v_cvt_pk_bf16_f32 v242, v154, v155
	v_cvt_pk_bf16_f32 v243, v156, v157
	s_nop 1
	v_permlane16_swap_b32_e32 v240, v242
	v_permlane16_swap_b32_e32 v241, v243
	global_store_dwordx4 v[248:249], v[240:243], off
	v_cvt_pk_bf16_f32 v244, v150, v151
	v_cvt_pk_bf16_f32 v245, v152, v153
	s_nop 0
	v_cvt_pk_bf16_f32 v246, v146, v147
	v_cvt_pk_bf16_f32 v247, v148, v149
	s_nop 1
	v_permlane16_swap_b32_e32 v244, v246
	v_permlane16_swap_b32_e32 v245, v247
	global_store_dwordx4 v[248:249], v[244:247], off offset:64
	v_mov_b64_e32 v[176:177], v[192:193]
	v_mov_b64_e32 v[196:197], v[194:195]
	v_pk_fma_f32 v[160:161], v[112:113], v[174:175], v[144:145] op_sel_hi:[1,0,1]
	v_pk_fma_f32 v[158:159], v[110:111], v[174:175], v[142:143] op_sel_hi:[1,0,1]
	v_pk_fma_f32 v[156:157], v[108:109], v[174:175], v[140:141] op_sel_hi:[1,0,1]
	v_pk_fma_f32 v[154:155], v[106:107], v[174:175], v[138:139] op_sel_hi:[1,0,1]
	v_pk_fma_f32 v[152:153], v[104:105], v[174:175], v[136:137] op_sel_hi:[1,0,1]
	v_pk_fma_f32 v[150:151], v[102:103], v[174:175], v[134:135] op_sel_hi:[1,0,1]
	v_pk_fma_f32 v[148:149], v[100:101], v[174:175], v[132:133] op_sel_hi:[1,0,1]
	s_and_b64 vcc, exec, s[42:43]
	v_pk_fma_f32 v[146:147], v[98:99], v[174:175], v[130:131] op_sel_hi:[1,0,1]
	s_cbranch_vccnz .LBB0_612
	v_add_co_u32_e32 v174, vcc, 0x2000, v196
	s_nop 1
	v_addc_co_u32_e32 v175, vcc, 0, v197, vcc
	v_mbcnt_lo_u32_b32 v228, -1, 0
	v_mbcnt_hi_u32_b32 v228, -1, v228
	v_and_b32_e32 v229, 15, v228
	v_lshrrev_b32_e32 v228, 4, v228
	v_mul_u32_u24_e32 v230, 0x110, v229
	v_lshl_add_u32 v222, v228, 4, v230
	v_add_u32_e32 v222, m0, v222
	v_mul_u32_u24_e32 v230, 0x110, v228
	v_lshl_add_u32 v224, v229, 4, v230
	v_add_u32_e32 v224, m0, v224
	v_sub_u32_e32 v236, v228, v229
	v_mul_i32_i24_e32 v236, 0x1f0, v236
	v_ashrrev_i32_e32 v237, 31, v236
	ds_write_b128 v222, v[158:161]
	ds_write_b128 v222, v[154:157] offset:64
	ds_write_b128 v222, v[150:153] offset:128
	ds_write_b128 v222, v[146:149] offset:192
	v_lshl_add_u64 v[236:237], v[174:175], 0, v[236:237]
	ds_read_b128 v[228:231], v224
	ds_read_b128 v[232:235], v224 offset:1088
	s_waitcnt lgkmcnt(1)
	global_store_dwordx4 v[236:237], v[228:231], off
	s_waitcnt lgkmcnt(0)
	global_store_dwordx4 v[236:237], v[232:235], off offset:2048
	v_add_co_u32_e32 v236, vcc, 0x1000, v236
	s_nop 1
	v_addc_co_u32_e32 v237, vcc, 0, v237, vcc
	ds_read_b128 v[228:231], v224 offset:2176
	ds_read_b128 v[232:235], v224 offset:3264
	s_waitcnt lgkmcnt(1)
	global_store_dwordx4 v[236:237], v[228:231], off
	s_waitcnt lgkmcnt(0)
	global_store_dwordx4 v[236:237], v[232:235], off offset:2048
.LBB0_612:
	v_cvt_pk_bf16_f32 v240, v158, v159
	v_cvt_pk_bf16_f32 v241, v160, v161
	v_add_co_u32_e32 v160, vcc, 0x1000, v176
	s_nop 1
	v_addc_co_u32_e32 v161, vcc, 0, v177, vcc
	v_mbcnt_lo_u32_b32 v0, -1, 0
	v_mbcnt_hi_u32_b32 v0, -1, v0
	v_bfe_u32 v0, v0, 4, 1
	v_mul_u32_u24_e32 v0, 24, v0
	v_lshl_add_u64 v[248:249], v[160:161], 0, v[0:1]
	v_cvt_pk_bf16_f32 v242, v154, v155
	v_cvt_pk_bf16_f32 v243, v156, v157
	s_nop 1
	v_permlane16_swap_b32_e32 v240, v242
	v_permlane16_swap_b32_e32 v241, v243
	global_store_dwordx4 v[248:249], v[240:243], off
	v_cvt_pk_bf16_f32 v244, v150, v151
	v_cvt_pk_bf16_f32 v245, v152, v153
	s_nop 0
	v_cvt_pk_bf16_f32 v246, v146, v147
	v_cvt_pk_bf16_f32 v247, v148, v149
	s_nop 1
	v_permlane16_swap_b32_e32 v244, v246
	v_permlane16_swap_b32_e32 v245, v247
	global_store_dwordx4 v[248:249], v[244:247], off offset:64
	v_mov_b64_e32 v[176:177], v[194:195]
	v_mov_b64_e32 v[174:175], v[192:193]
	v_pk_fma_f32 v[160:161], v[96:97], v[172:173], v[144:145] op_sel_hi:[1,0,1]
	v_pk_fma_f32 v[158:159], v[94:95], v[172:173], v[142:143] op_sel_hi:[1,0,1]
	v_pk_fma_f32 v[148:149], v[92:93], v[172:173], v[140:141] op_sel_hi:[1,0,1]
	v_pk_fma_f32 v[146:147], v[90:91], v[172:173], v[138:139] op_sel_hi:[1,0,1]
	v_pk_fma_f32 v[152:153], v[88:89], v[172:173], v[136:137] op_sel_hi:[1,0,1]
	v_pk_fma_f32 v[150:151], v[86:87], v[172:173], v[134:135] op_sel_hi:[1,0,1]
	v_pk_fma_f32 v[156:157], v[84:85], v[172:173], v[132:133] op_sel_hi:[1,0,1]
	s_and_b64 vcc, exec, s[42:43]
	v_pk_fma_f32 v[154:155], v[82:83], v[172:173], v[130:131] op_sel_hi:[1,0,1]
	s_cbranch_vccnz .LBB0_614
	v_add_co_u32_e32 v172, vcc, 0x4000, v176
	s_nop 1
	v_addc_co_u32_e32 v173, vcc, 0, v177, vcc
	v_mbcnt_lo_u32_b32 v228, -1, 0
	v_mbcnt_hi_u32_b32 v228, -1, v228
	v_and_b32_e32 v229, 15, v228
	v_lshrrev_b32_e32 v228, 4, v228
	v_mul_u32_u24_e32 v230, 0x110, v229
	v_lshl_add_u32 v222, v228, 4, v230
	v_add_u32_e32 v222, m0, v222
	v_mul_u32_u24_e32 v230, 0x110, v228
	v_lshl_add_u32 v224, v229, 4, v230
	v_add_u32_e32 v224, m0, v224
	v_sub_u32_e32 v236, v228, v229
	v_mul_i32_i24_e32 v236, 0x1f0, v236
	v_ashrrev_i32_e32 v237, 31, v236
	ds_write_b128 v222, v[158:161]
	ds_write_b128 v222, v[146:149] offset:64
	ds_write_b128 v222, v[150:153] offset:128
	ds_write_b128 v222, v[154:157] offset:192
	v_lshl_add_u64 v[236:237], v[172:173], 0, v[236:237]
	ds_read_b128 v[228:231], v224
	ds_read_b128 v[232:235], v224 offset:1088
	s_waitcnt lgkmcnt(1)
	global_store_dwordx4 v[236:237], v[228:231], off
	s_waitcnt lgkmcnt(0)
	global_store_dwordx4 v[236:237], v[232:235], off offset:2048
	v_add_co_u32_e32 v236, vcc, 0x1000, v236
	s_nop 1
	v_addc_co_u32_e32 v237, vcc, 0, v237, vcc
	ds_read_b128 v[228:231], v224 offset:2176
	ds_read_b128 v[232:235], v224 offset:3264
	s_waitcnt lgkmcnt(1)
	global_store_dwordx4 v[236:237], v[228:231], off
	s_waitcnt lgkmcnt(0)
	global_store_dwordx4 v[236:237], v[232:235], off offset:2048
.LBB0_614:
	v_cvt_pk_bf16_f32 v240, v158, v159
	v_cvt_pk_bf16_f32 v241, v160, v161
	v_add_co_u32_e32 v160, vcc, 0x2000, v174
	v_mov_b64_e32 v[172:173], v[192:193]
	s_nop 0
	v_addc_co_u32_e32 v161, vcc, 0, v175, vcc
	v_mbcnt_lo_u32_b32 v0, -1, 0
	v_mbcnt_hi_u32_b32 v0, -1, v0
	v_bfe_u32 v0, v0, 4, 1
	v_mul_u32_u24_e32 v0, 24, v0
	v_lshl_add_u64 v[248:249], v[160:161], 0, v[0:1]
	v_cvt_pk_bf16_f32 v242, v146, v147
	v_cvt_pk_bf16_f32 v243, v148, v149
	s_nop 1
	v_permlane16_swap_b32_e32 v240, v242
	v_permlane16_swap_b32_e32 v241, v243
	global_store_dwordx4 v[248:249], v[240:243], off
	v_cvt_pk_bf16_f32 v244, v150, v151
	v_cvt_pk_bf16_f32 v245, v152, v153
	s_nop 0
	v_cvt_pk_bf16_f32 v246, v154, v155
	v_cvt_pk_bf16_f32 v247, v156, v157
	s_nop 1
	v_permlane16_swap_b32_e32 v244, v246
	v_permlane16_swap_b32_e32 v245, v247
	global_store_dwordx4 v[248:249], v[244:247], off offset:64
	v_mov_b64_e32 v[174:175], v[194:195]
	v_pk_fma_f32 v[160:161], v[80:81], v[170:171], v[144:145] op_sel_hi:[1,0,1]
	v_pk_fma_f32 v[158:159], v[78:79], v[170:171], v[142:143] op_sel_hi:[1,0,1]
	v_pk_fma_f32 v[156:157], v[76:77], v[170:171], v[140:141] op_sel_hi:[1,0,1]
	v_pk_fma_f32 v[154:155], v[74:75], v[170:171], v[138:139] op_sel_hi:[1,0,1]
	v_pk_fma_f32 v[152:153], v[72:73], v[170:171], v[136:137] op_sel_hi:[1,0,1]
	v_pk_fma_f32 v[150:151], v[70:71], v[170:171], v[134:135] op_sel_hi:[1,0,1]
	v_pk_fma_f32 v[148:149], v[68:69], v[170:171], v[132:133] op_sel_hi:[1,0,1]
	s_and_b64 vcc, exec, s[42:43]
	v_pk_fma_f32 v[146:147], v[66:67], v[170:171], v[130:131] op_sel_hi:[1,0,1]
	s_cbranch_vccnz .LBB0_616
	v_add_co_u32_e32 v170, vcc, 0x6000, v174
	s_nop 1
	v_addc_co_u32_e32 v171, vcc, 0, v175, vcc
	v_mbcnt_lo_u32_b32 v228, -1, 0
	v_mbcnt_hi_u32_b32 v228, -1, v228
	v_and_b32_e32 v229, 15, v228
	v_lshrrev_b32_e32 v228, 4, v228
	v_mul_u32_u24_e32 v230, 0x110, v229
	v_lshl_add_u32 v222, v228, 4, v230
	v_add_u32_e32 v222, m0, v222
	v_mul_u32_u24_e32 v230, 0x110, v228
	v_lshl_add_u32 v224, v229, 4, v230
	v_add_u32_e32 v224, m0, v224
	v_sub_u32_e32 v236, v228, v229
	v_mul_i32_i24_e32 v236, 0x1f0, v236
	v_ashrrev_i32_e32 v237, 31, v236
	ds_write_b128 v222, v[158:161]
	ds_write_b128 v222, v[154:157] offset:64
	ds_write_b128 v222, v[150:153] offset:128
	ds_write_b128 v222, v[146:149] offset:192
	v_lshl_add_u64 v[236:237], v[170:171], 0, v[236:237]
	ds_read_b128 v[228:231], v224
	ds_read_b128 v[232:235], v224 offset:1088
	s_waitcnt lgkmcnt(1)
	global_store_dwordx4 v[236:237], v[228:231], off
	s_waitcnt lgkmcnt(0)
	global_store_dwordx4 v[236:237], v[232:235], off offset:2048
	v_add_co_u32_e32 v236, vcc, 0x1000, v236
	s_nop 1
	v_addc_co_u32_e32 v237, vcc, 0, v237, vcc
	ds_read_b128 v[228:231], v224 offset:2176
	ds_read_b128 v[232:235], v224 offset:3264
	s_waitcnt lgkmcnt(1)
	global_store_dwordx4 v[236:237], v[228:231], off
	s_waitcnt lgkmcnt(0)
	global_store_dwordx4 v[236:237], v[232:235], off offset:2048
.LBB0_616:
	v_cvt_pk_bf16_f32 v240, v158, v159
	v_cvt_pk_bf16_f32 v241, v160, v161
	v_add_co_u32_e32 v160, vcc, 0x3000, v172
	s_nop 1
	v_addc_co_u32_e32 v161, vcc, 0, v173, vcc
	v_mbcnt_lo_u32_b32 v0, -1, 0
	v_mbcnt_hi_u32_b32 v0, -1, v0
	v_bfe_u32 v0, v0, 4, 1
	v_mul_u32_u24_e32 v0, 24, v0
	v_lshl_add_u64 v[248:249], v[160:161], 0, v[0:1]
	v_cvt_pk_bf16_f32 v242, v154, v155
	v_cvt_pk_bf16_f32 v243, v156, v157
	s_nop 1
	v_permlane16_swap_b32_e32 v240, v242
	v_permlane16_swap_b32_e32 v241, v243
	global_store_dwordx4 v[248:249], v[240:243], off
	v_cvt_pk_bf16_f32 v244, v150, v151
	v_cvt_pk_bf16_f32 v245, v152, v153
	s_nop 0
	v_cvt_pk_bf16_f32 v246, v146, v147
	v_cvt_pk_bf16_f32 v247, v148, v149
	s_nop 1
	v_permlane16_swap_b32_e32 v244, v246
	v_permlane16_swap_b32_e32 v245, v247
	global_store_dwordx4 v[248:249], v[244:247], off offset:64
	v_mov_b64_e32 v[170:171], v[192:193]
	v_mov_b64_e32 v[172:173], v[194:195]
	v_pk_fma_f32 v[160:161], v[64:65], v[168:169], v[144:145] op_sel_hi:[1,0,1]
	v_pk_fma_f32 v[158:159], v[62:63], v[168:169], v[142:143] op_sel_hi:[1,0,1]
	v_pk_fma_f32 v[148:149], v[60:61], v[168:169], v[140:141] op_sel_hi:[1,0,1]
	v_pk_fma_f32 v[146:147], v[58:59], v[168:169], v[138:139] op_sel_hi:[1,0,1]
	v_pk_fma_f32 v[152:153], v[56:57], v[168:169], v[136:137] op_sel_hi:[1,0,1]
	v_pk_fma_f32 v[150:151], v[54:55], v[168:169], v[134:135] op_sel_hi:[1,0,1]
	v_pk_fma_f32 v[156:157], v[52:53], v[168:169], v[132:133] op_sel_hi:[1,0,1]
	s_and_b64 vcc, exec, s[42:43]
	v_pk_fma_f32 v[154:155], v[50:51], v[168:169], v[130:131] op_sel_hi:[1,0,1]
	s_cbranch_vccnz .LBB0_618
	v_add_co_u32_e32 v168, vcc, 0x10000, v172
	s_nop 1
	v_addc_co_u32_e32 v169, vcc, 0, v173, vcc
	v_mbcnt_lo_u32_b32 v228, -1, 0
	v_mbcnt_hi_u32_b32 v228, -1, v228
	v_and_b32_e32 v229, 15, v228
	v_lshrrev_b32_e32 v228, 4, v228
	v_mul_u32_u24_e32 v230, 0x110, v229
	v_lshl_add_u32 v222, v228, 4, v230
	v_add_u32_e32 v222, m0, v222
	v_mul_u32_u24_e32 v230, 0x110, v228
	v_lshl_add_u32 v224, v229, 4, v230
	v_add_u32_e32 v224, m0, v224
	v_sub_u32_e32 v236, v228, v229
	v_mul_i32_i24_e32 v236, 0x1f0, v236
	v_ashrrev_i32_e32 v237, 31, v236
	ds_write_b128 v222, v[158:161]
	ds_write_b128 v222, v[146:149] offset:64
	ds_write_b128 v222, v[150:153] offset:128
	ds_write_b128 v222, v[154:157] offset:192
	v_lshl_add_u64 v[236:237], v[168:169], 0, v[236:237]
	ds_read_b128 v[228:231], v224
	ds_read_b128 v[232:235], v224 offset:1088
	s_waitcnt lgkmcnt(1)
	global_store_dwordx4 v[236:237], v[228:231], off
	s_waitcnt lgkmcnt(0)
	global_store_dwordx4 v[236:237], v[232:235], off offset:2048
	v_add_co_u32_e32 v236, vcc, 0x1000, v236
	s_nop 1
	v_addc_co_u32_e32 v237, vcc, 0, v237, vcc
	ds_read_b128 v[228:231], v224 offset:2176
	ds_read_b128 v[232:235], v224 offset:3264
	s_waitcnt lgkmcnt(1)
	global_store_dwordx4 v[236:237], v[228:231], off
	s_waitcnt lgkmcnt(0)
	global_store_dwordx4 v[236:237], v[232:235], off offset:2048
.LBB0_618:
	v_cvt_pk_bf16_f32 v240, v158, v159
	v_cvt_pk_bf16_f32 v241, v160, v161
	v_add_co_u32_e32 v160, vcc, 0x8000, v170
	v_mov_b64_e32 v[168:169], v[192:193]
	s_nop 0
	v_addc_co_u32_e32 v161, vcc, 0, v171, vcc
	v_mbcnt_lo_u32_b32 v0, -1, 0
	v_mbcnt_hi_u32_b32 v0, -1, v0
	v_bfe_u32 v0, v0, 4, 1
	v_mul_u32_u24_e32 v0, 24, v0
	v_lshl_add_u64 v[248:249], v[160:161], 0, v[0:1]
	v_cvt_pk_bf16_f32 v242, v146, v147
	v_cvt_pk_bf16_f32 v243, v148, v149
	s_nop 1
	v_permlane16_swap_b32_e32 v240, v242
	v_permlane16_swap_b32_e32 v241, v243
	global_store_dwordx4 v[248:249], v[240:243], off
	v_cvt_pk_bf16_f32 v244, v150, v151
	v_cvt_pk_bf16_f32 v245, v152, v153
	s_nop 0
	v_cvt_pk_bf16_f32 v246, v154, v155
	v_cvt_pk_bf16_f32 v247, v156, v157
	s_nop 1
	v_permlane16_swap_b32_e32 v244, v246
	v_permlane16_swap_b32_e32 v245, v247
	global_store_dwordx4 v[248:249], v[244:247], off offset:64
	v_mov_b64_e32 v[170:171], v[194:195]
	v_pk_fma_f32 v[160:161], v[48:49], v[166:167], v[144:145] op_sel_hi:[1,0,1]
	v_pk_fma_f32 v[158:159], v[46:47], v[166:167], v[142:143] op_sel_hi:[1,0,1]
	v_pk_fma_f32 v[156:157], v[44:45], v[166:167], v[140:141] op_sel_hi:[1,0,1]
	v_pk_fma_f32 v[154:155], v[42:43], v[166:167], v[138:139] op_sel_hi:[1,0,1]
	v_pk_fma_f32 v[152:153], v[40:41], v[166:167], v[136:137] op_sel_hi:[1,0,1]
	v_pk_fma_f32 v[150:151], v[38:39], v[166:167], v[134:135] op_sel_hi:[1,0,1]
	v_pk_fma_f32 v[148:149], v[36:37], v[166:167], v[132:133] op_sel_hi:[1,0,1]
	s_and_b64 vcc, exec, s[42:43]
	v_pk_fma_f32 v[146:147], v[34:35], v[166:167], v[130:131] op_sel_hi:[1,0,1]
	s_cbranch_vccnz .LBB0_620
	v_add_co_u32_e32 v166, vcc, 0x12000, v170
	s_nop 1
	v_addc_co_u32_e32 v167, vcc, 0, v171, vcc
	v_mbcnt_lo_u32_b32 v228, -1, 0
	v_mbcnt_hi_u32_b32 v228, -1, v228
	v_and_b32_e32 v229, 15, v228
	v_lshrrev_b32_e32 v228, 4, v228
	v_mul_u32_u24_e32 v230, 0x110, v229
	v_lshl_add_u32 v222, v228, 4, v230
	v_add_u32_e32 v222, m0, v222
	v_mul_u32_u24_e32 v230, 0x110, v228
	v_lshl_add_u32 v224, v229, 4, v230
	v_add_u32_e32 v224, m0, v224
	v_sub_u32_e32 v236, v228, v229
	v_mul_i32_i24_e32 v236, 0x1f0, v236
	v_ashrrev_i32_e32 v237, 31, v236
	ds_write_b128 v222, v[158:161]
	ds_write_b128 v222, v[154:157] offset:64
	ds_write_b128 v222, v[150:153] offset:128
	ds_write_b128 v222, v[146:149] offset:192
	v_lshl_add_u64 v[236:237], v[166:167], 0, v[236:237]
	ds_read_b128 v[228:231], v224
	ds_read_b128 v[232:235], v224 offset:1088
	s_waitcnt lgkmcnt(1)
	global_store_dwordx4 v[236:237], v[228:231], off
	s_waitcnt lgkmcnt(0)
	global_store_dwordx4 v[236:237], v[232:235], off offset:2048
	v_add_co_u32_e32 v236, vcc, 0x1000, v236
	s_nop 1
	v_addc_co_u32_e32 v237, vcc, 0, v237, vcc
	ds_read_b128 v[228:231], v224 offset:2176
	ds_read_b128 v[232:235], v224 offset:3264
	s_waitcnt lgkmcnt(1)
	global_store_dwordx4 v[236:237], v[228:231], off
	s_waitcnt lgkmcnt(0)
	global_store_dwordx4 v[236:237], v[232:235], off offset:2048
.LBB0_620:
	v_cvt_pk_bf16_f32 v240, v158, v159
	v_cvt_pk_bf16_f32 v241, v160, v161
	v_add_co_u32_e32 v160, vcc, 0x9000, v168
	s_nop 1
	v_addc_co_u32_e32 v161, vcc, 0, v169, vcc
	v_mbcnt_lo_u32_b32 v0, -1, 0
	v_mbcnt_hi_u32_b32 v0, -1, v0
	v_bfe_u32 v0, v0, 4, 1
	v_mul_u32_u24_e32 v0, 24, v0
	v_lshl_add_u64 v[248:249], v[160:161], 0, v[0:1]
	v_cvt_pk_bf16_f32 v242, v154, v155
	v_cvt_pk_bf16_f32 v243, v156, v157
	s_nop 1
	v_permlane16_swap_b32_e32 v240, v242
	v_permlane16_swap_b32_e32 v241, v243
	global_store_dwordx4 v[248:249], v[240:243], off
	v_cvt_pk_bf16_f32 v244, v150, v151
	v_cvt_pk_bf16_f32 v245, v152, v153
	s_nop 0
	v_cvt_pk_bf16_f32 v246, v146, v147
	v_cvt_pk_bf16_f32 v247, v148, v149
	s_nop 1
	v_permlane16_swap_b32_e32 v244, v246
	v_permlane16_swap_b32_e32 v245, v247
	global_store_dwordx4 v[248:249], v[244:247], off offset:64
	v_mov_b64_e32 v[168:169], v[194:195]
	v_mov_b64_e32 v[166:167], v[192:193]
	v_pk_fma_f32 v[160:161], v[32:33], v[164:165], v[144:145] op_sel_hi:[1,0,1]
	v_pk_fma_f32 v[158:159], v[30:31], v[164:165], v[142:143] op_sel_hi:[1,0,1]
	v_pk_fma_f32 v[148:149], v[28:29], v[164:165], v[140:141] op_sel_hi:[1,0,1]
	v_pk_fma_f32 v[146:147], v[26:27], v[164:165], v[138:139] op_sel_hi:[1,0,1]
	v_pk_fma_f32 v[152:153], v[24:25], v[164:165], v[136:137] op_sel_hi:[1,0,1]
	v_pk_fma_f32 v[150:151], v[22:23], v[164:165], v[134:135] op_sel_hi:[1,0,1]
	v_pk_fma_f32 v[156:157], v[20:21], v[164:165], v[132:133] op_sel_hi:[1,0,1]
	s_and_b64 vcc, exec, s[42:43]
	v_pk_fma_f32 v[154:155], v[18:19], v[164:165], v[130:131] op_sel_hi:[1,0,1]
	s_cbranch_vccnz .LBB0_622
	v_add_co_u32_e32 v164, vcc, 0x14000, v168
	s_nop 1
	v_addc_co_u32_e32 v165, vcc, 0, v169, vcc
	v_mbcnt_lo_u32_b32 v228, -1, 0
	v_mbcnt_hi_u32_b32 v228, -1, v228
	v_and_b32_e32 v229, 15, v228
	v_lshrrev_b32_e32 v228, 4, v228
	v_mul_u32_u24_e32 v230, 0x110, v229
	v_lshl_add_u32 v222, v228, 4, v230
	v_add_u32_e32 v222, m0, v222
	v_mul_u32_u24_e32 v230, 0x110, v228
	v_lshl_add_u32 v224, v229, 4, v230
	v_add_u32_e32 v224, m0, v224
	v_sub_u32_e32 v236, v228, v229
	v_mul_i32_i24_e32 v236, 0x1f0, v236
	v_ashrrev_i32_e32 v237, 31, v236
	ds_write_b128 v222, v[158:161]
	ds_write_b128 v222, v[146:149] offset:64
	ds_write_b128 v222, v[150:153] offset:128
	ds_write_b128 v222, v[154:157] offset:192
	v_lshl_add_u64 v[236:237], v[164:165], 0, v[236:237]
	ds_read_b128 v[228:231], v224
	ds_read_b128 v[232:235], v224 offset:1088
	s_waitcnt lgkmcnt(1)
	global_store_dwordx4 v[236:237], v[228:231], off
	s_waitcnt lgkmcnt(0)
	global_store_dwordx4 v[236:237], v[232:235], off offset:2048
	v_add_co_u32_e32 v236, vcc, 0x1000, v236
	s_nop 1
	v_addc_co_u32_e32 v237, vcc, 0, v237, vcc
	ds_read_b128 v[228:231], v224 offset:2176
	ds_read_b128 v[232:235], v224 offset:3264
	s_waitcnt lgkmcnt(1)
	global_store_dwordx4 v[236:237], v[228:231], off
	s_waitcnt lgkmcnt(0)
	global_store_dwordx4 v[236:237], v[232:235], off offset:2048
.LBB0_622:
	v_cvt_pk_bf16_f32 v240, v158, v159
	v_cvt_pk_bf16_f32 v241, v160, v161
	v_add_co_u32_e32 v160, vcc, 0xa000, v166
	v_pk_fma_f32 v[144:145], v[16:17], v[162:163], v[144:145] op_sel_hi:[1,0,1]
	s_nop 0
	v_addc_co_u32_e32 v161, vcc, 0, v167, vcc
	v_mbcnt_lo_u32_b32 v0, -1, 0
	v_mbcnt_hi_u32_b32 v0, -1, v0
	v_bfe_u32 v0, v0, 4, 1
	v_mul_u32_u24_e32 v0, 24, v0
	v_lshl_add_u64 v[248:249], v[160:161], 0, v[0:1]
	v_cvt_pk_bf16_f32 v242, v146, v147
	v_cvt_pk_bf16_f32 v243, v148, v149
	s_nop 1
	v_permlane16_swap_b32_e32 v240, v242
	v_permlane16_swap_b32_e32 v241, v243
	global_store_dwordx4 v[248:249], v[240:243], off
	v_cvt_pk_bf16_f32 v244, v150, v151
	v_cvt_pk_bf16_f32 v245, v152, v153
	s_nop 0
	v_cvt_pk_bf16_f32 v246, v154, v155
	v_cvt_pk_bf16_f32 v247, v156, v157
	s_nop 1
	v_permlane16_swap_b32_e32 v244, v246
	v_permlane16_swap_b32_e32 v245, v247
	global_store_dwordx4 v[248:249], v[244:247], off offset:64
	v_mov_b64_e32 v[148:149], v[194:195]
	v_mov_b64_e32 v[146:147], v[192:193]
	v_pk_fma_f32 v[142:143], v[14:15], v[162:163], v[142:143] op_sel_hi:[1,0,1]
	v_pk_fma_f32 v[140:141], v[12:13], v[162:163], v[140:141] op_sel_hi:[1,0,1]
	v_pk_fma_f32 v[138:139], v[10:11], v[162:163], v[138:139] op_sel_hi:[1,0,1]
	v_pk_fma_f32 v[136:137], v[8:9], v[162:163], v[136:137] op_sel_hi:[1,0,1]
	v_pk_fma_f32 v[134:135], v[6:7], v[162:163], v[134:135] op_sel_hi:[1,0,1]
	v_pk_fma_f32 v[132:133], v[4:5], v[162:163], v[132:133] op_sel_hi:[1,0,1]
	s_and_b64 vcc, exec, s[42:43]
	v_pk_fma_f32 v[130:131], v[2:3], v[162:163], v[130:131] op_sel_hi:[1,0,1]
	s_cbranch_vccnz .LBB0_624
	v_add_co_u32_e32 v148, vcc, 0x16000, v148
	s_nop 1
	v_addc_co_u32_e32 v149, vcc, 0, v149, vcc
	v_mbcnt_lo_u32_b32 v228, -1, 0
	v_mbcnt_hi_u32_b32 v228, -1, v228
	v_and_b32_e32 v229, 15, v228
	v_lshrrev_b32_e32 v228, 4, v228
	v_mul_u32_u24_e32 v230, 0x110, v229
	v_lshl_add_u32 v222, v228, 4, v230
	v_add_u32_e32 v222, m0, v222
	v_mul_u32_u24_e32 v230, 0x110, v228
	v_lshl_add_u32 v224, v229, 4, v230
	v_add_u32_e32 v224, m0, v224
	v_sub_u32_e32 v236, v228, v229
	v_mul_i32_i24_e32 v236, 0x1f0, v236
	v_ashrrev_i32_e32 v237, 31, v236
	ds_write_b128 v222, v[142:145]
	ds_write_b128 v222, v[138:141] offset:64
	ds_write_b128 v222, v[134:137] offset:128
	ds_write_b128 v222, v[130:133] offset:192
	v_lshl_add_u64 v[236:237], v[148:149], 0, v[236:237]
	ds_read_b128 v[228:231], v224
	ds_read_b128 v[232:235], v224 offset:1088
	s_waitcnt lgkmcnt(1)
	global_store_dwordx4 v[236:237], v[228:231], off
	s_waitcnt lgkmcnt(0)
	global_store_dwordx4 v[236:237], v[232:235], off offset:2048
	v_add_co_u32_e32 v236, vcc, 0x1000, v236
	s_nop 1
	v_addc_co_u32_e32 v237, vcc, 0, v237, vcc
	ds_read_b128 v[228:231], v224 offset:2176
	ds_read_b128 v[232:235], v224 offset:3264
	s_waitcnt lgkmcnt(1)
	global_store_dwordx4 v[236:237], v[228:231], off
	s_waitcnt lgkmcnt(0)
	global_store_dwordx4 v[236:237], v[232:235], off offset:2048

.LBB0_628:
	s_and_b64 vcc, exec, s[42:43]
	s_cbranch_vccnz .LBB0_630
	v_mbcnt_lo_u32_b32 v228, -1, 0
	v_mbcnt_hi_u32_b32 v228, -1, v228
	v_and_b32_e32 v229, 15, v228
	v_lshrrev_b32_e32 v228, 4, v228
	v_mul_u32_u24_e32 v230, 0x110, v229
	v_lshl_add_u32 v222, v228, 4, v230
	v_add_u32_e32 v222, m0, v222
	v_mul_u32_u24_e32 v230, 0x110, v228
	v_lshl_add_u32 v224, v229, 4, v230
	v_add_u32_e32 v224, m0, v224
	v_sub_u32_e32 v236, v228, v229
	v_mul_i32_i24_e32 v236, 0x1f0, v236
	v_ashrrev_i32_e32 v237, 31, v236
	ds_write_b128 v222, v[170:173]
	ds_write_b128 v222, v[174:177] offset:64
	ds_write_b128 v222, v[162:165] offset:128
	ds_write_b128 v222, v[166:169] offset:192
	v_lshl_add_u64 v[236:237], v[212:213], 0, v[236:237]
	ds_read_b128 v[228:231], v224
	ds_read_b128 v[232:235], v224 offset:1088
	s_waitcnt lgkmcnt(1)
	global_store_dwordx4 v[236:237], v[228:231], off
	s_waitcnt lgkmcnt(0)
	global_store_dwordx4 v[236:237], v[232:235], off offset:2048
	v_add_co_u32_e32 v236, vcc, 0x1000, v236
	s_nop 1
	v_addc_co_u32_e32 v237, vcc, 0, v237, vcc
	ds_read_b128 v[228:231], v224 offset:2176
	ds_read_b128 v[232:235], v224 offset:3264
	s_waitcnt lgkmcnt(1)
	global_store_dwordx4 v[236:237], v[228:231], off
	s_waitcnt lgkmcnt(0)
	global_store_dwordx4 v[236:237], v[232:235], off offset:2048

.LBB0_632:
	s_and_b64 vcc, exec, s[42:43]
	s_cbranch_vccnz .LBB0_634
	v_add_co_u32_e32 v210, vcc, 0x2000, v210
	s_nop 1
	v_addc_co_u32_e32 v211, vcc, 0, v211, vcc
	v_mbcnt_lo_u32_b32 v228, -1, 0
	v_mbcnt_hi_u32_b32 v228, -1, v228
	v_and_b32_e32 v229, 15, v228
	v_lshrrev_b32_e32 v228, 4, v228
	v_mul_u32_u24_e32 v230, 0x110, v229
	v_lshl_add_u32 v222, v228, 4, v230
	v_add_u32_e32 v222, m0, v222
	v_mul_u32_u24_e32 v230, 0x110, v228
	v_lshl_add_u32 v224, v229, 4, v230
	v_add_u32_e32 v224, m0, v224
	v_sub_u32_e32 v236, v228, v229
	v_mul_i32_i24_e32 v236, 0x1f0, v236
	v_ashrrev_i32_e32 v237, 31, v236
	ds_write_b128 v222, v[170:173]
	ds_write_b128 v222, v[166:169] offset:64
	ds_write_b128 v222, v[162:165] offset:128
	ds_write_b128 v222, v[174:177] offset:192
	v_lshl_add_u64 v[236:237], v[210:211], 0, v[236:237]
	ds_read_b128 v[228:231], v224
	ds_read_b128 v[232:235], v224 offset:1088
	s_waitcnt lgkmcnt(1)
	global_store_dwordx4 v[236:237], v[228:231], off
	s_waitcnt lgkmcnt(0)
	global_store_dwordx4 v[236:237], v[232:235], off offset:2048
	v_add_co_u32_e32 v236, vcc, 0x1000, v236
	s_nop 1
	v_addc_co_u32_e32 v237, vcc, 0, v237, vcc
	ds_read_b128 v[228:231], v224 offset:2176
	ds_read_b128 v[232:235], v224 offset:3264
	s_waitcnt lgkmcnt(1)
	global_store_dwordx4 v[236:237], v[228:231], off
	s_waitcnt lgkmcnt(0)
	global_store_dwordx4 v[236:237], v[232:235], off offset:2048

.LBB0_636:
	s_and_b64 vcc, exec, s[42:43]
	s_cbranch_vccnz .LBB0_638
	v_add_co_u32_e32 v208, vcc, 0x4000, v208
	s_nop 1
	v_addc_co_u32_e32 v209, vcc, 0, v209, vcc
	v_mbcnt_lo_u32_b32 v228, -1, 0
	v_mbcnt_hi_u32_b32 v228, -1, v228
	v_and_b32_e32 v229, 15, v228
	v_lshrrev_b32_e32 v228, 4, v228
	v_mul_u32_u24_e32 v230, 0x110, v229
	v_lshl_add_u32 v222, v228, 4, v230
	v_add_u32_e32 v222, m0, v222
	v_mul_u32_u24_e32 v230, 0x110, v228
	v_lshl_add_u32 v224, v229, 4, v230
	v_add_u32_e32 v224, m0, v224
	v_sub_u32_e32 v236, v228, v229
	v_mul_i32_i24_e32 v236, 0x1f0, v236
	v_ashrrev_i32_e32 v237, 31, v236
	ds_write_b128 v222, v[170:173]
	ds_write_b128 v222, v[166:169] offset:64
	ds_write_b128 v222, v[162:165] offset:128
	ds_write_b128 v222, v[174:177] offset:192
	v_lshl_add_u64 v[236:237], v[208:209], 0, v[236:237]
	ds_read_b128 v[228:231], v224
	ds_read_b128 v[232:235], v224 offset:1088
	s_waitcnt lgkmcnt(1)
	global_store_dwordx4 v[236:237], v[228:231], off
	s_waitcnt lgkmcnt(0)
	global_store_dwordx4 v[236:237], v[232:235], off offset:2048
	v_add_co_u32_e32 v236, vcc, 0x1000, v236
	s_nop 1
	v_addc_co_u32_e32 v237, vcc, 0, v237, vcc
	ds_read_b128 v[228:231], v224 offset:2176
	ds_read_b128 v[232:235], v224 offset:3264
	s_waitcnt lgkmcnt(1)
	global_store_dwordx4 v[236:237], v[228:231], off
	s_waitcnt lgkmcnt(0)
	global_store_dwordx4 v[236:237], v[232:235], off offset:2048

.LBB0_640:
	s_and_b64 vcc, exec, s[42:43]
	s_cbranch_vccnz .LBB0_642
	v_add_co_u32_e32 v206, vcc, 0x6000, v206
	s_nop 1
	v_addc_co_u32_e32 v207, vcc, 0, v207, vcc
	v_mbcnt_lo_u32_b32 v228, -1, 0
	v_mbcnt_hi_u32_b32 v228, -1, v228
	v_and_b32_e32 v229, 15, v228
	v_lshrrev_b32_e32 v228, 4, v228
	v_mul_u32_u24_e32 v230, 0x110, v229
	v_lshl_add_u32 v222, v228, 4, v230
	v_add_u32_e32 v222, m0, v222
	v_mul_u32_u24_e32 v230, 0x110, v228
	v_lshl_add_u32 v224, v229, 4, v230
	v_add_u32_e32 v224, m0, v224
	v_sub_u32_e32 v236, v228, v229
	v_mul_i32_i24_e32 v236, 0x1f0, v236
	v_ashrrev_i32_e32 v237, 31, v236
	ds_write_b128 v222, v[170:173]
	ds_write_b128 v222, v[166:169] offset:64
	ds_write_b128 v222, v[162:165] offset:128
	ds_write_b128 v222, v[174:177] offset:192
	v_lshl_add_u64 v[236:237], v[206:207], 0, v[236:237]
	ds_read_b128 v[228:231], v224
	ds_read_b128 v[232:235], v224 offset:1088
	s_waitcnt lgkmcnt(1)
	global_store_dwordx4 v[236:237], v[228:231], off
	s_waitcnt lgkmcnt(0)
	global_store_dwordx4 v[236:237], v[232:235], off offset:2048
	v_add_co_u32_e32 v236, vcc, 0x1000, v236
	s_nop 1
	v_addc_co_u32_e32 v237, vcc, 0, v237, vcc
	ds_read_b128 v[228:231], v224 offset:2176
	ds_read_b128 v[232:235], v224 offset:3264
	s_waitcnt lgkmcnt(1)
	global_store_dwordx4 v[236:237], v[228:231], off
	s_waitcnt lgkmcnt(0)
	global_store_dwordx4 v[236:237], v[232:235], off offset:2048

.LBB0_644:
	s_and_b64 vcc, exec, s[42:43]
	s_cbranch_vccnz .LBB0_646
	v_add_co_u32_e32 v204, vcc, 0x10000, v204
	s_nop 1
	v_addc_co_u32_e32 v205, vcc, 0, v205, vcc
	v_mbcnt_lo_u32_b32 v228, -1, 0
	v_mbcnt_hi_u32_b32 v228, -1, v228
	v_and_b32_e32 v229, 15, v228
	v_lshrrev_b32_e32 v228, 4, v228
	v_mul_u32_u24_e32 v230, 0x110, v229
	v_lshl_add_u32 v222, v228, 4, v230
	v_add_u32_e32 v222, m0, v222
	v_mul_u32_u24_e32 v230, 0x110, v228
	v_lshl_add_u32 v224, v229, 4, v230
	v_add_u32_e32 v224, m0, v224
	v_sub_u32_e32 v236, v228, v229
	v_mul_i32_i24_e32 v236, 0x1f0, v236
	v_ashrrev_i32_e32 v237, 31, v236
	ds_write_b128 v222, v[170:173]
	ds_write_b128 v222, v[166:169] offset:64
	ds_write_b128 v222, v[162:165] offset:128
	ds_write_b128 v222, v[174:177] offset:192
	v_lshl_add_u64 v[236:237], v[204:205], 0, v[236:237]
	ds_read_b128 v[228:231], v224
	ds_read_b128 v[232:235], v224 offset:1088
	s_waitcnt lgkmcnt(1)
	global_store_dwordx4 v[236:237], v[228:231], off
	s_waitcnt lgkmcnt(0)
	global_store_dwordx4 v[236:237], v[232:235], off offset:2048
	v_add_co_u32_e32 v236, vcc, 0x1000, v236
	s_nop 1
	v_addc_co_u32_e32 v237, vcc, 0, v237, vcc
	ds_read_b128 v[228:231], v224 offset:2176
	ds_read_b128 v[232:235], v224 offset:3264
	s_waitcnt lgkmcnt(1)
	global_store_dwordx4 v[236:237], v[228:231], off
	s_waitcnt lgkmcnt(0)
	global_store_dwordx4 v[236:237], v[232:235], off offset:2048

.LBB0_648:
	s_and_b64 vcc, exec, s[42:43]
	s_cbranch_vccnz .LBB0_650
	v_add_co_u32_e32 v202, vcc, 0x12000, v202
	s_nop 1
	v_addc_co_u32_e32 v203, vcc, 0, v203, vcc
	v_mbcnt_lo_u32_b32 v228, -1, 0
	v_mbcnt_hi_u32_b32 v228, -1, v228
	v_and_b32_e32 v229, 15, v228
	v_lshrrev_b32_e32 v228, 4, v228
	v_mul_u32_u24_e32 v230, 0x110, v229
	v_lshl_add_u32 v222, v228, 4, v230
	v_add_u32_e32 v222, m0, v222
	v_mul_u32_u24_e32 v230, 0x110, v228
	v_lshl_add_u32 v224, v229, 4, v230
	v_add_u32_e32 v224, m0, v224
	v_sub_u32_e32 v236, v228, v229
	v_mul_i32_i24_e32 v236, 0x1f0, v236
	v_ashrrev_i32_e32 v237, 31, v236
	ds_write_b128 v222, v[170:173]
	ds_write_b128 v222, v[166:169] offset:64
	ds_write_b128 v222, v[162:165] offset:128
	ds_write_b128 v222, v[174:177] offset:192
	v_lshl_add_u64 v[236:237], v[202:203], 0, v[236:237]
	ds_read_b128 v[228:231], v224
	ds_read_b128 v[232:235], v224 offset:1088
	s_waitcnt lgkmcnt(1)
	global_store_dwordx4 v[236:237], v[228:231], off
	s_waitcnt lgkmcnt(0)
	global_store_dwordx4 v[236:237], v[232:235], off offset:2048
	v_add_co_u32_e32 v236, vcc, 0x1000, v236
	s_nop 1
	v_addc_co_u32_e32 v237, vcc, 0, v237, vcc
	ds_read_b128 v[228:231], v224 offset:2176
	ds_read_b128 v[232:235], v224 offset:3264
	s_waitcnt lgkmcnt(1)
	global_store_dwordx4 v[236:237], v[228:231], off
	s_waitcnt lgkmcnt(0)
	global_store_dwordx4 v[236:237], v[232:235], off offset:2048

.LBB0_652:
	s_and_b64 vcc, exec, s[42:43]
	v_mov_b32_e32 v225, v226
	s_cbranch_vccnz .LBB0_654
	v_add_co_u32_e32 v200, vcc, 0x14000, v200
	s_nop 1
	v_addc_co_u32_e32 v201, vcc, 0, v201, vcc
	v_mbcnt_lo_u32_b32 v228, -1, 0
	v_mbcnt_hi_u32_b32 v228, -1, v228
	v_and_b32_e32 v229, 15, v228
	v_lshrrev_b32_e32 v228, 4, v228
	v_mul_u32_u24_e32 v230, 0x110, v229
	v_lshl_add_u32 v222, v228, 4, v230
	v_add_u32_e32 v222, m0, v222
	v_mul_u32_u24_e32 v230, 0x110, v228
	v_lshl_add_u32 v224, v229, 4, v230
	v_add_u32_e32 v224, m0, v224
	v_sub_u32_e32 v236, v228, v229
	v_mul_i32_i24_e32 v236, 0x1f0, v236
	v_ashrrev_i32_e32 v237, 31, v236
	ds_write_b128 v222, v[174:177]
	ds_write_b128 v222, v[170:173] offset:64
	ds_write_b128 v222, v[166:169] offset:128
	ds_write_b128 v222, v[162:165] offset:192
	v_lshl_add_u64 v[236:237], v[200:201], 0, v[236:237]
	ds_read_b128 v[228:231], v224
	ds_read_b128 v[232:235], v224 offset:1088
	s_waitcnt lgkmcnt(1)
	global_store_dwordx4 v[236:237], v[228:231], off
	s_waitcnt lgkmcnt(0)
	global_store_dwordx4 v[236:237], v[232:235], off offset:2048
	v_add_co_u32_e32 v236, vcc, 0x1000, v236
	s_nop 1
	v_addc_co_u32_e32 v237, vcc, 0, v237, vcc
	ds_read_b128 v[228:231], v224 offset:2176
	ds_read_b128 v[232:235], v224 offset:3264
	s_waitcnt lgkmcnt(1)
	global_store_dwordx4 v[236:237], v[228:231], off
	s_waitcnt lgkmcnt(0)
	global_store_dwordx4 v[236:237], v[232:235], off offset:2048

.LBB0_656:
	s_and_b64 vcc, exec, s[42:43]
	s_cbranch_vccnz .LBB0_658
	v_add_co_u32_e32 v142, vcc, 0x16000, v194
	s_nop 1
	v_addc_co_u32_e32 v143, vcc, 0, v195, vcc
	v_mbcnt_lo_u32_b32 v228, -1, 0
	v_mbcnt_hi_u32_b32 v228, -1, v228
	v_and_b32_e32 v229, 15, v228
	v_lshrrev_b32_e32 v228, 4, v228
	v_mul_u32_u24_e32 v230, 0x110, v229
	v_lshl_add_u32 v222, v228, 4, v230
	v_add_u32_e32 v222, m0, v222
	v_mul_u32_u24_e32 v230, 0x110, v228
	v_lshl_add_u32 v224, v229, 4, v230
	v_add_u32_e32 v224, m0, v224
	v_sub_u32_e32 v236, v228, v229
	v_mul_i32_i24_e32 v236, 0x1f0, v236
	v_ashrrev_i32_e32 v237, 31, v236
	ds_write_b128 v222, v[146:149]
	ds_write_b128 v222, v[134:137] offset:64
	ds_write_b128 v222, v[130:133] offset:128
	ds_write_b128 v222, v[138:141] offset:192
	v_lshl_add_u64 v[236:237], v[142:143], 0, v[236:237]
	ds_read_b128 v[228:231], v224
	ds_read_b128 v[232:235], v224 offset:1088
	s_waitcnt lgkmcnt(1)
	global_store_dwordx4 v[236:237], v[228:231], off
	s_waitcnt lgkmcnt(0)
	global_store_dwordx4 v[236:237], v[232:235], off offset:2048
	v_add_co_u32_e32 v236, vcc, 0x1000, v236
	s_nop 1
	v_addc_co_u32_e32 v237, vcc, 0, v237, vcc
	ds_read_b128 v[228:231], v224 offset:2176
	ds_read_b128 v[232:235], v224 offset:3264
	s_waitcnt lgkmcnt(1)
	global_store_dwordx4 v[236:237], v[228:231], off
	s_waitcnt lgkmcnt(0)
	global_store_dwordx4 v[236:237], v[232:235], off offset:2048
